# same loop, head placed 40 bytes later (code placement only)
# speedup vs baseline: 1.0078x; 1.0061x over previous
.LBB5_820:
	v_lshlrev_b32_e32 v32, 1, v202
	v_and_b32_e32 v185, 32, v32
	v_lshlrev_b32_e32 v33, 8, v204
	s_movk_i32 s0, 0xc0
	v_add_u32_e32 v32, 0, v185
	v_and_or_b32 v187, v206, s0, v33
	v_add3_u32 v212, v32, v205, v187
	v_max3_f32 v32, v16, v17, v0
	v_max3_f32 v33, v18, v19, v1
	s_waitcnt vmcnt(0) lgkmcnt(0)
	s_barrier
	s_cmp_lg_u32 0, -1
	v_max3_f32 v32, v32, v2, v3
	v_max3_f32 v33, v33, v22, v23
	s_mov_b32 s48, 1
	v_max3_f32 v32, v32, v20, v21
	v_max3_f32 v33, v33, v6, v7
	s_mov_b32 s3, 0
	v_max3_f32 v32, v32, v4, v5
	v_max3_f32 v33, v33, v26, v27
	s_nop 0
	v_max3_f32 v32, v32, v24, v25
	v_max3_f32 v33, v33, v10, v11
	s_nop 0
	v_max3_f32 v32, v32, v8, v9
	v_max3_f32 v33, v33, v30, v31
	s_nop 0
	v_max3_f32 v32, v32, v28, v29
	v_max3_f32 v33, v33, v14, v15
	s_nop 0
	v_max3_f32 v32, v32, v12, v13
	s_nop 0
	v_max_f32_e32 v32, v32, v33
	s_nop 0
	v_mov_b32_e32 v33, v32
	s_nop 1
	v_permlane32_swap_b32_e32 v32, v33
	v_max_f32_e32 v32, v32, v33
	s_nop 0
	v_sub_f32_e32 v0, v0, v32
	v_sub_f32_e32 v1, v1, v32
	v_sub_f32_e32 v16, v16, v32
	v_sub_f32_e32 v17, v17, v32
	v_sub_f32_e32 v18, v18, v32
	v_sub_f32_e32 v2, v2, v32
	s_nop 0
	v_exp_f32_e32 v64, v0
	v_exp_f32_e32 v65, v1
	v_lshl_add_u64 v[0:1], v[188:189], 0, s[58:59]
	s_mov_b32 s0, m0
	s_mov_b32 m0, s64
	s_nop 0
	global_load_lds_dwordx4 v[0:1], off
	s_mov_b32 m0, s0
	s_cselect_b32 s0, 0, 0
	s_add_i32 s24, s0, s63
	v_lshl_add_u64 v[0:1], v[190:191], 0, s[82:83]
	s_add_i32 s0, s24, 0xa000
	s_mov_b32 s1, m0
	s_mov_b32 m0, s0
	s_nop 0
	global_load_lds_dwordx4 v[0:1], off
	s_mov_b32 m0, s1
	s_mov_b64 s[0:1], 0x20080
	v_lshl_add_u64 v[0:1], v[190:191], 0, s[0:1]
	s_add_i32 s24, s24, 0xc000
	s_mov_b32 s0, m0
	s_mov_b32 m0, s24
	s_nop 0
	global_load_lds_dwordx4 v[0:1], off
	s_mov_b32 m0, s0
	ds_read_b128 v[172:175], v208 offset:8192
	ds_read_b128 v[160:163], v208 offset:8704
	ds_read_b128 v[168:171], v208 offset:10240
	ds_read_b128 v[152:155], v208 offset:10752
	ds_read_b128 v[164:167], v208 offset:12288
	ds_read_b128 v[148:151], v208 offset:12800
	ds_read_b128 v[156:159], v208 offset:14336
	ds_read_b128 v[144:147], v208 offset:14848
	v_sub_f32_e32 v19, v19, v32
	v_sub_f32_e32 v3, v3, v32
	v_sub_f32_e32 v20, v20, v32
	v_sub_f32_e32 v4, v4, v32
	v_sub_f32_e32 v21, v21, v32
	v_sub_f32_e32 v5, v5, v32
	v_sub_f32_e32 v22, v22, v32
	v_sub_f32_e32 v6, v6, v32
	v_sub_f32_e32 v23, v23, v32
	v_sub_f32_e32 v7, v7, v32
	v_sub_f32_e32 v24, v24, v32
	v_sub_f32_e32 v8, v8, v32
	v_sub_f32_e32 v25, v25, v32
	v_sub_f32_e32 v9, v9, v32
	v_sub_f32_e32 v26, v26, v32
	v_sub_f32_e32 v10, v10, v32
	v_sub_f32_e32 v27, v27, v32
	v_sub_f32_e32 v11, v11, v32
	v_sub_f32_e32 v28, v28, v32
	v_sub_f32_e32 v12, v12, v32
	v_sub_f32_e32 v29, v29, v32
	v_sub_f32_e32 v13, v13, v32
	v_sub_f32_e32 v30, v30, v32
	v_sub_f32_e32 v14, v14, v32
	v_sub_f32_e32 v31, v31, v32
	v_sub_f32_e32 v15, v15, v32
	v_exp_f32_e32 v80, v16
	v_exp_f32_e32 v81, v17
	v_exp_f32_e32 v82, v18
	v_exp_f32_e32 v83, v19
	v_exp_f32_e32 v84, v20
	v_exp_f32_e32 v85, v21
	v_exp_f32_e32 v86, v22
	v_exp_f32_e32 v87, v23
	v_exp_f32_e32 v88, v24
	v_exp_f32_e32 v89, v25
	v_exp_f32_e32 v90, v26
	v_exp_f32_e32 v91, v27
	v_exp_f32_e32 v92, v28
	v_exp_f32_e32 v93, v29
	v_exp_f32_e32 v94, v30
	v_exp_f32_e32 v95, v31
	v_exp_f32_e32 v66, v2
	v_exp_f32_e32 v67, v3
	v_exp_f32_e32 v68, v4
	v_exp_f32_e32 v69, v5
	v_exp_f32_e32 v70, v6
	v_exp_f32_e32 v71, v7
	v_exp_f32_e32 v72, v8
	v_exp_f32_e32 v73, v9
	v_exp_f32_e32 v74, v10
	v_exp_f32_e32 v75, v11
	v_exp_f32_e32 v76, v12
	v_exp_f32_e32 v77, v13
	v_exp_f32_e32 v78, v14
	v_exp_f32_e32 v79, v15
	s_waitcnt vmcnt(3) lgkmcnt(0)
	s_barrier
	s_cmp_lt_i32 s17, 7
	v_cmp_gt_u32_e64 s[0:1], 32, v202
	v_add_f32_e32 v211, v179, v32
	s_cbranch_scc1 .LBB5_836
	v_mov_b32_e32 v16, v179
	v_mov_b32_e32 v17, v179
	v_mov_b32_e32 v30, v179
	v_mov_b32_e32 v31, v179
	s_mov_b64 s[12:13], 0xa0000
	v_mov_b32_e32 v18, v179
	v_mov_b32_e32 v19, v179
	v_mov_b32_e32 v20, v179
	v_mov_b32_e32 v21, v179
	v_mov_b32_e32 v22, v179
	v_mov_b32_e32 v23, v179
	v_mov_b32_e32 v24, v179
	v_mov_b32_e32 v25, v179
	v_mov_b32_e32 v26, v179
	v_mov_b32_e32 v27, v179
	v_mov_b32_e32 v28, v179
	v_mov_b32_e32 v29, v179
	v_mov_b64_e32 v[62:63], v[30:31]
	v_mov_b64_e32 v[46:47], v[30:31]
	v_mov_b64_e32 v[0:1], v[16:17]
	s_add_i32 s30, s17, -5
	v_lshl_add_u64 v[194:195], v[192:193], 0, s[58:59]
	v_lshl_add_u64 v[196:197], v[190:191], 0, s[58:59]
	v_lshl_add_u64 v[198:199], v[188:189], 0, s[12:13]
	s_mov_b32 s34, 0
	s_movk_i32 s3, 0x4000
	s_movk_i32 s33, 0x2000
	v_mov_b32_e32 v214, 0
	v_mov_b64_e32 v[60:61], v[28:29]
	v_mov_b64_e32 v[58:59], v[26:27]
	v_mov_b64_e32 v[56:57], v[24:25]
	v_mov_b64_e32 v[54:55], v[22:23]
	v_mov_b64_e32 v[52:53], v[20:21]
	v_mov_b64_e32 v[50:51], v[18:19]
	v_mov_b64_e32 v[48:49], v[16:17]
	v_mov_b64_e32 v[44:45], v[28:29]
	v_mov_b64_e32 v[42:43], v[26:27]
	v_mov_b64_e32 v[40:41], v[24:25]
	v_mov_b64_e32 v[38:39], v[22:23]
	v_mov_b64_e32 v[36:37], v[20:21]
	v_mov_b64_e32 v[34:35], v[18:19]
	v_mov_b64_e32 v[32:33], v[16:17]
	v_mov_b64_e32 v[2:3], v[18:19]
	v_mov_b64_e32 v[4:5], v[20:21]
	v_mov_b64_e32 v[6:7], v[22:23]
	v_mov_b64_e32 v[8:9], v[24:25]
	v_mov_b64_e32 v[10:11], v[26:27]
	v_mov_b64_e32 v[12:13], v[28:29]
	v_mov_b64_e32 v[14:15], v[30:31]
	s_mov_b32 s32, m0
	v_xor_b32_e32 v220, 0x80000000, v211
	v_mov_b32_e32 v221, v220
	v_mov_b32_e32 v222, v220
	v_mov_b32_e32 v223, v220
	v_mov_b32_e32 v224, v220
	v_mov_b32_e32 v225, v220
	v_mov_b32_e32 v226, v220
	v_mov_b32_e32 v227, v220
	v_mov_b32_e32 v228, v220
	v_mov_b32_e32 v229, v220
	v_mov_b32_e32 v230, v220
	v_mov_b32_e32 v231, v220
	v_mov_b32_e32 v232, v220
	v_mov_b32_e32 v233, v220
	v_mov_b32_e32 v234, v220
	v_mov_b32_e32 v235, v220
	v_add_u32_e32 v216, s80, v184
	s_lshl_b32 s99, s34, 1
	v_add_u32_e32 v183, s99, v212
	v_add_u32_e32 v215, s3, v208
	v_add_f32_e32 v251, v80, v81
	ds_read_b128 v[236:239], v207
	ds_read_b128 v[240:243], v207 offset:1024
	ds_read_b128 v[244:247], v207 offset:2048
	ds_read_b128 v[252:255], v207 offset:3072
	s_waitcnt lgkmcnt(0)
	s_nop 0
	s_nop 0
	s_nop 0
	s_nop 0
	s_nop 0
	s_nop 0
	s_nop 0
	s_nop 0
	s_nop 0
	s_nop 0

.LBB5_835:
	s_or_b64 exec, exec, s[50:51]
	v_add_f32_e32 v211, v211, v109
	v_mul_f32_e32 v214, v214, v108
	s_branch .LBB5_826
	s_nop 0
	s_nop 0
	s_nop 0
	s_nop 0
	s_nop 0
	s_nop 0
